# bh2 variant: RG-LRU prompt units moved into phase +4 (mixed with SSD, 50/50 blocks), phase +5 = sample scan + post only
# baseline (speedup 1.0000x reference)
; #define SUB(k, bit) (!(kargs()->li == 1 && (k) == lo) || ((kargs()->submask >> (bit)) & 1u))
; __global__ void __launch_bounds__(NWAVES * 64, 2) fwd(Args args_unused) {
;     ...
;         if (IN(pb + 4)) {
;             PH_PTRS PH_LAYER
;             if (SUB(pb + 4, 0)) {
;                 const bf16* wg = (const bf16*)(wl + WL_G); const int qq = lane & 15, q4 = lane >> 4;
;                 for (int un = gw; un < 16 * 8 * 4; un += NGW) {
;                     const int rt = un >> 5, j = (un >> 2) & 7, qd = un & 3, ch0 = j * 128 + 32 * qd;
;                     const bf16* ap = XCV + ((size_t)NPROMPT + 16 * rt + qq) * DM + j * 128 + 8 * q4;
;                     f32x4 ga[4];
; #pragma unroll
;                     for (int ct = 0; ct < 4; ++ct) ga[ct] = (f32x4){0.f, 0.f, 0.f, 0.f};
; #pragma unroll
;                     for (int ks = 0; ks < 4; ++ks) { const bf16x8 xf = *(const bf16x8*)(ap + 32 * ks);
; #pragma unroll
;                         for (int ct = 0; ct < 4; ++ct) { const int wrow = j * 256 + (ct >> 1) * 128 + 32 * qd + 16 * (ct & 1) + qq;
;                             ga[ct] = __builtin_amdgcn_mfma_f32_16x16x32_bf16(*(const bf16x8*)(wg + (size_t)wrow * 128 + 32 * ks + 8 * q4), xf, ga[ct], 0, 0, 0); } }
; #pragma unroll
;                     for (int h2 = 0; h2 < 2; ++h2) { const int ch = ch0 + 16 * h2 + 4 * q4; const size_t row = (size_t)16 * rt + qq;
;                         const f32x4 brv = *(const f32x4*)(A->in[I_BR] + l * DM + ch), biv = *(const f32x4*)(A->in[I_BI] + l * DM + ch), sp = *(const f32x4*)((const float*)(ws + WS_SPL) + l * DM + ch);
.LBB0_1574:
	s_mov_b32 s100, 0
	s_mov_b32 s101, 0
	s_cmp_lt_i32 s84, 8
	s_cselect_b64 s[0:1], -1, 0
	s_and_b64 s[28:29], s[0:1], s[4:5]
	s_andn2_b64 vcc, exec, s[28:29]
	s_cbranch_vccnz .LBB0_1754
	v_readlane_b32 s99, v254, 3
	s_nop 3
	s_lshr_b32 s99, s99, 3
	s_and_b32 s99, s99, 1
	s_mov_b32 s98, 2
	s_cmp_eq_u32 s99, 1
	s_cselect_b32 s98, 0, s98
	s_cmp_lg_u32 s98, 0
	s_cbranch_scc1 .Lm2_go_0
	s_cmp_lt_i32 s84, 9
	s_cbranch_scc0 .Lm2_go_0
	s_cmp_gt_i32 s85, 8
	s_cbranch_scc0 .Lm2_go_0
	s_mov_b64 s[0:1], -1
	s_mov_b32 s101, 2
	s_branch .LBB0_1808
.Lm2_retB_0:
	s_mov_b32 s100, 1
	s_mov_b32 s101, 0
	s_mov_b64 s[28:29], -1
.Lm2_go_0:
	s_mov_b64 s[52:53], s[82:83]
	s_mov_b32 s33, 0
	s_load_dwordx4 s[92:95], s[52:53], 0x140
	v_readlane_b32 s68, v254, 3
	s_mov_b32 s0, s2
	s_load_dword s3, s[82:83], 0x168
	s_waitcnt lgkmcnt(0)
	v_mov_b32_e32 v102, v0
	v_writelane_b32 v254, s3, 12
	s_lshl_b32 s0, s68, 3
	v_readfirstlane_b32 s3, v102
	s_ashr_i32 s20, s3, 6
	s_add_i32 s21, s20, s0
	v_bfe_u32 v31, v102, 4, 2
	s_mov_b32 s1, 0
	v_and_b32_e32 v32, 15, v102
	s_cmpk_gt_i32 s21, 0x1ff
	v_lshlrev_b32_e32 v30, 3, v31
	v_lshlrev_b32_e32 v34, 4, v31
	v_lshlrev_b32_e32 v33, 2, v31
	s_cbranch_scc1 .LBB0_1610
	v_readlane_b32 s18, v254, 12
	s_lshl_b32 s22, s18, 3
	s_add_u32 s4, s94, 0x53900000
	s_addc_u32 s5, s95, 0
	v_mov_b32_e32 v37, 0
	s_add_u32 s6, s94, 0x63d00000
	v_mov_b32_e32 v35, v37
	s_addc_u32 s7, s95, 0
	v_lshl_add_u64 v[2:3], s[94:95], 0, v[34:35]
	s_mov_b64 s[10:11], 0x4300000
	s_add_u32 s8, s94, 0x63f00000
	v_lshl_add_u64 v[38:39], v[2:3], 0, s[10:11]
	s_load_dwordx2 s[10:11], s[52:53], 0xf0
	s_load_dwordx2 s[12:13], s[52:53], 0x100
	s_mov_b64 s[16:17], 0x4300040
	s_addc_u32 s9, s95, 0
	v_lshl_add_u64 v[40:41], v[2:3], 0, s[16:17]
	s_mov_b64 s[16:17], 0x4300080
	s_add_u32 s14, s94, 0xb080000
	v_lshl_add_u64 v[42:43], v[2:3], 0, s[16:17]
	s_mov_b64 s[16:17], 0x43000c0
	s_addc_u32 s15, s95, 0
	v_lshl_add_u64 v[44:45], v[2:3], 0, s[16:17]
	s_lshl_b32 s0, s68, 8
	s_lshl_b32 s16, s20, 5
	s_add_i32 s23, s0, s16
	s_lshl_b32 s24, s18, 8
	v_lshlrev_b32_e32 v46, 1, v30
	v_mov_b32_e32 v47, v37
	s_mov_b64 s[16:17], 0x4000000
	s_mov_b32 s25, 0xbecccccd
	v_mov_b32_e32 v1, 0x3c088889
	s_branch .LBB0_1578

; #define SEAM(k) do { if (IN(k) && IN((k) + 1)) { KArgs Ab = kargs(); XcdBarrier bar_; bar_.bar = (unsigned*)(Ab->ws + WS_CTL) + CW_BAR + Ab->li * XCD_BAR_WORDS; bar_.x = xb_xcc_id(); bar_.st = MISC + 8; xcd_barrier(bar_, (int)threadIdx.x); } } while (0)
; #define SUB(k, bit) (!(kargs()->li == 1 && (k) == lo) || ((kargs()->submask >> (bit)) & 1u))
; __global__ void __launch_bounds__(NWAVES * 64, 2) fwd(Args args_unused) {
;     ...
;         SEAM(pb + 4);
;         if (IN(pb + 5)) {
;             PH_PTRS PH_LAYER
;             if (SUB(pb + 5, 0)) {
.LBB0_1754:
	s_and_b64 vcc, exec, s[28:29]
	s_cbranch_vccz .Lm2_done_0
	s_cmp_lg_u32 s100, 0
	s_cbranch_scc1 .Lm2_done_0
	s_cmp_lt_i32 s84, 9
	s_cbranch_scc0 .Lm2_done_0
	s_cmp_gt_i32 s85, 8
	s_cbranch_scc0 .Lm2_done_0
	s_mov_b64 s[0:1], -1
	s_mov_b32 s101, 1
	s_branch .LBB0_1808

; #define LAS __attribute__((address_space(3)))
; #define SUB(k, bit) (!(kargs()->li == 1 && (k) == lo) || ((kargs()->submask >> (bit)) & 1u))
; __global__ void __launch_bounds__(NWAVES * 64, 2) fwd(Args args_unused) {
;     ...
;         if (IN(pb + 5)) {
;             PH_PTRS PH_LAYER
;             if (SUB(pb + 5, 0)) {
;                 constexpr int LT = 136, AS = 68;
;                 LAS bf16* Xs = (LAS bf16*)lds;
;                 LAS bf16* Ws = Xs + 128 * LT;
;                 LAS float* As = (LAS float*)(Ws + 128 * LT);
;                 LAS float* Us = As + 128 * AS;
;                 LAS float* sP = Us + 128 * AS;
;                 LAS float* sH = sP + 512;
;                 LAS float* cS = sH + 512;
;                 LAS float* cst = cS + 128;
;                 static_assert(2 * 128 * LT * 2 + (2 * 128 * AS + 512 + 512 + 128 + 192) * 4 <= LDSCTL_OFF, "LRU LDS map");
;                 const int qq = lane & 15, q4 = lane >> 4, w = wave;
;                 for (int un = vcu; un < 256; un += G) {
.LBB0_1808:
	s_cmp_lt_i32 s84, 9
	s_cselect_b64 s[4:5], -1, 0
	s_and_b64 s[0:1], s[4:5], s[0:1]
	s_andn2_b64 vcc, exec, s[0:1]
	s_cbranch_vccnz .LBB0_1930
	s_mov_b64 s[34:35], s[82:83]
	s_load_dwordx4 s[28:31], s[34:35], 0x140
	s_mov_b32 s6, 0
	s_load_dword s3, s[82:83], 0x168
	v_readlane_b32 s33, v254, 3
	s_mov_b32 s63, s2
	v_mov_b32_e32 v126, v0
	s_waitcnt lgkmcnt(0)
	s_add_u32 s26, s30, 0x1d200000
	s_addc_u32 s27, s31, 0
	v_ashrrev_i32_e32 v144, 6, v126
	s_mov_b32 s41, 0
	v_and_b32_e32 v1, 63, v126
	s_cmpk_gt_i32 s33, 0xff
	v_readfirstlane_b32 s62, v144
	s_cselect_b32 s99, 1, 0
	s_cmp_lg_u32 s101, 0
	s_cbranch_scc1 .Lm2_run_0
	s_cmp_lg_u32 s100, 0
	s_cbranch_scc1 .LBB0_1918

; #define SUB(k, bit) (!(kargs()->li == 1 && (k) == lo) || ((kargs()->submask >> (bit)) & 1u))
; __global__ void __launch_bounds__(NWAVES * 64, 2) fwd(Args args_unused) {
;     ...
;         if (IN(pb + 4)) {
;             PH_PTRS PH_LAYER
;             if (SUB(pb + 4, 0)) {
;                 const bf16* wg = (const bf16*)(wl + WL_G); const int qq = lane & 15, q4 = lane >> 4;
;                 for (int un = gw; un < 16 * 8 * 4; un += NGW) {
;                     const int rt = un >> 5, j = (un >> 2) & 7, qd = un & 3, ch0 = j * 128 + 32 * qd;
;                     const bf16* ap = XCV + ((size_t)NPROMPT + 16 * rt + qq) * DM + j * 128 + 8 * q4;
;                     f32x4 ga[4];
; #pragma unroll
;                     for (int ct = 0; ct < 4; ++ct) ga[ct] = (f32x4){0.f, 0.f, 0.f, 0.f};
; #pragma unroll
;                     for (int ks = 0; ks < 4; ++ks) { const bf16x8 xf = *(const bf16x8*)(ap + 32 * ks);
; #pragma unroll
;                         for (int ct = 0; ct < 4; ++ct) { const int wrow = j * 256 + (ct >> 1) * 128 + 32 * qd + 16 * (ct & 1) + qq;
;                             ga[ct] = __builtin_amdgcn_mfma_f32_16x16x32_bf16(*(const bf16x8*)(wg + (size_t)wrow * 128 + 32 * ks + 8 * q4), xf, ga[ct], 0, 0, 0); } }
; #pragma unroll
;                     for (int h2 = 0; h2 < 2; ++h2) { const int ch = ch0 + 16 * h2 + 4 * q4; const size_t row = (size_t)16 * rt + qq;
;                         const f32x4 brv = *(const f32x4*)(A->in[I_BR] + l * DM + ch), biv = *(const f32x4*)(A->in[I_BI] + l * DM + ch), sp = *(const f32x4*)((const float*)(ws + WS_SPL) + l * DM + ch);
.LBB0_3599:
	s_mov_b32 s100, 0
	s_mov_b32 s101, 0
	s_cmp_lt_i32 s84, 18
	s_cselect_b64 s[0:1], -1, 0
	s_and_b64 s[4:5], s[0:1], s[4:5]
	s_andn2_b64 vcc, exec, s[4:5]
	s_cbranch_vccnz .LBB0_3778
	v_readlane_b32 s99, v254, 3
	s_nop 3
	s_lshr_b32 s99, s99, 3
	s_and_b32 s99, s99, 1
	s_mov_b32 s98, 2
	s_cmp_eq_u32 s99, 1
	s_cselect_b32 s98, 0, s98
	s_cmp_lg_u32 s98, 0
	s_cbranch_scc1 .Lm2_go_1
	s_cmp_lt_i32 s84, 19
	s_cbranch_scc0 .Lm2_go_1
	s_cmp_gt_i32 s85, 18
	s_cbranch_scc0 .Lm2_go_1
	s_mov_b64 s[0:1], -1
	s_mov_b32 s101, 2
	s_branch .LBB0_3832
.Lm2_retB_1:
	s_mov_b32 s100, 1
	s_mov_b32 s101, 0
	s_mov_b64 s[4:5], -1
.Lm2_go_1:
	v_writelane_b32 v254, s4, 13
	s_mov_b64 s[52:53], s[82:83]
	s_mov_b32 s33, 0
	v_writelane_b32 v254, s5, 14
	s_load_dwordx4 s[92:95], s[52:53], 0x140
	s_load_dword s3, s[82:83], 0x168
	v_readlane_b32 s68, v254, 3
	s_mov_b32 s0, s2
	s_waitcnt lgkmcnt(0)
	v_mov_b32_e32 v102, v0
	v_writelane_b32 v254, s3, 12
	s_lshl_b32 s0, s68, 3
	v_readfirstlane_b32 s3, v102
	s_ashr_i32 s20, s3, 6
	s_add_i32 s21, s20, s0
	v_bfe_u32 v31, v102, 4, 2
	s_mov_b32 s1, 0
	v_and_b32_e32 v32, 15, v102
	s_cmpk_gt_i32 s21, 0x1ff
	v_lshlrev_b32_e32 v30, 3, v31
	v_lshlrev_b32_e32 v34, 4, v31
	v_lshlrev_b32_e32 v33, 2, v31
	s_cbranch_scc1 .LBB0_3635
	v_readlane_b32 s18, v254, 12
	s_lshl_b32 s22, s18, 3
	s_add_u32 s4, s94, 0x53900000
	s_addc_u32 s5, s95, 0
	s_add_u32 s6, s94, 0x63d00000
	s_load_dwordx2 s[10:11], s[52:53], 0xf0
	s_load_dwordx2 s[12:13], s[52:53], 0x100
	s_addc_u32 s7, s95, 0
	s_add_u32 s8, s94, 0x63f00000
	s_addc_u32 s9, s95, 0
	v_mov_b32_e32 v37, 0
	s_waitcnt lgkmcnt(0)
	s_add_u32 s10, s10, 0x1000
	v_mov_b32_e32 v35, v37
	s_addc_u32 s11, s11, 0
	v_lshl_add_u64 v[2:3], s[94:95], 0, v[34:35]
	s_add_u32 s12, s12, 0x1000
	s_mov_b64 s[16:17], 0x8800040
	s_mov_b64 s[14:15], 0x8800000
	s_addc_u32 s13, s13, 0
	v_lshl_add_u64 v[40:41], v[2:3], 0, s[16:17]
	s_mov_b64 s[16:17], 0x8800080
	v_lshl_add_u64 v[38:39], v[2:3], 0, s[14:15]
	s_add_u32 s14, s94, 0xb081000
	v_lshl_add_u64 v[42:43], v[2:3], 0, s[16:17]
	s_mov_b64 s[16:17], 0x88000c0
	s_addc_u32 s15, s95, 0
	v_lshl_add_u64 v[44:45], v[2:3], 0, s[16:17]
	s_lshl_b32 s0, s68, 8
	s_lshl_b32 s16, s20, 5
	s_add_i32 s23, s0, s16
	s_lshl_b32 s24, s18, 8
	v_lshlrev_b32_e32 v46, 1, v30
	v_mov_b32_e32 v47, v37
	s_mov_b64 s[16:17], 0x4000000
	s_mov_b32 s25, 0xbecccccd
	v_mov_b32_e32 v1, 0x3c088889
	s_branch .LBB0_3603

; #define SEAM(k) do { if (IN(k) && IN((k) + 1)) { KArgs Ab = kargs(); XcdBarrier bar_; bar_.bar = (unsigned*)(Ab->ws + WS_CTL) + CW_BAR + Ab->li * XCD_BAR_WORDS; bar_.x = xb_xcc_id(); bar_.st = MISC + 8; xcd_barrier(bar_, (int)threadIdx.x); } } while (0)
; #define SUB(k, bit) (!(kargs()->li == 1 && (k) == lo) || ((kargs()->submask >> (bit)) & 1u))
; __global__ void __launch_bounds__(NWAVES * 64, 2) fwd(Args args_unused) {
;     ...
;         SEAM(pb + 4);
;         if (IN(pb + 5)) {
;             PH_PTRS PH_LAYER
;             if (SUB(pb + 5, 0)) {
.LBB0_3778:
	s_and_b64 vcc, exec, s[4:5]
	s_cbranch_vccz .Lm2_done_1
	s_cmp_lg_u32 s100, 0
	s_cbranch_scc1 .Lm2_done_1
	s_cmp_lt_i32 s84, 19
	s_cbranch_scc0 .Lm2_done_1
	s_cmp_gt_i32 s85, 18
	s_cbranch_scc0 .Lm2_done_1
	s_mov_b64 s[0:1], -1
	s_mov_b32 s101, 1
	s_branch .LBB0_3832

; #define LAS __attribute__((address_space(3)))
; #define SUB(k, bit) (!(kargs()->li == 1 && (k) == lo) || ((kargs()->submask >> (bit)) & 1u))
; __global__ void __launch_bounds__(NWAVES * 64, 2) fwd(Args args_unused) {
;     ...
;         if (IN(pb + 5)) {
;             PH_PTRS PH_LAYER
;             if (SUB(pb + 5, 0)) {
;                 constexpr int LT = 136, AS = 68;
;                 LAS bf16* Xs = (LAS bf16*)lds;
;                 LAS bf16* Ws = Xs + 128 * LT;
;                 LAS float* As = (LAS float*)(Ws + 128 * LT);
;                 LAS float* Us = As + 128 * AS;
;                 LAS float* sP = Us + 128 * AS;
;                 LAS float* sH = sP + 512;
;                 LAS float* cS = sH + 512;
;                 LAS float* cst = cS + 128;
;                 static_assert(2 * 128 * LT * 2 + (2 * 128 * AS + 512 + 512 + 128 + 192) * 4 <= LDSCTL_OFF, "LRU LDS map");
;                 const int qq = lane & 15, q4 = lane >> 4, w = wave;
;                 for (int un = vcu; un < 256; un += G) {
.LBB0_3832:
	s_cmp_lt_i32 s84, 19
	s_cselect_b64 s[4:5], -1, 0
	s_and_b64 s[0:1], s[4:5], s[0:1]
	s_andn2_b64 vcc, exec, s[0:1]
	s_cbranch_vccnz .LBB0_3954
	s_mov_b64 s[34:35], s[82:83]
	s_load_dwordx4 s[28:31], s[34:35], 0x140
	s_mov_b32 s6, 0
	s_mov_b32 s63, s2
	s_load_dword s3, s[82:83], 0x168
	v_readlane_b32 s33, v254, 3
	v_mov_b32_e32 v126, v0
	s_waitcnt lgkmcnt(0)
	s_add_u32 s26, s30, 0x1d200000
	s_addc_u32 s27, s31, 0
	v_ashrrev_i32_e32 v144, 6, v126
	s_mov_b32 s41, 0
	v_and_b32_e32 v1, 63, v126
	s_cmpk_gt_i32 s33, 0xff
	v_readfirstlane_b32 s62, v144
	s_cselect_b32 s99, 1, 0
	s_cmp_lg_u32 s101, 0
	s_cbranch_scc1 .Lm2_run_1
	s_cmp_lg_u32 s100, 0
	s_cbranch_scc1 .LBB0_3942
